# slc loop: stabiliser-free fast body too (sel mask applied to packed P)
# speedup vs baseline: 1.0186x; 1.0009x over previous
.LBB0_1327:
	v_and_b32_e32 v38, 63, v36
	v_lshrrev_b32_e32 v39, 5, v38
	v_lshrrev_b32_e32 v40, 1, v36
	v_bitop3_b32 v39, v40, v39, 1 bitop3:0x6c
	v_lshlrev_b32_e32 v111, 4, v39
	v_bfe_u32 v39, v36, 2, 2
	v_lshl_add_u64 v[100:101], v[0:1], 1, s[12:13]
	v_lshrrev_b32_e32 v0, 3, v36
	v_and_b32_e32 v116, 4, v0
	v_and_or_b32 v0, v37, 4, v39
	v_lshlrev_b32_e32 v117, 7, v0
	v_lshlrev_b32_e32 v0, 1, v38
	s_add_u32 s16, s10, -1
	s_waitcnt lgkmcnt(0)
	s_barrier
	v_and_b32_e32 v118, 32, v0
	v_lshlrev_b32_e32 v0, 3, v38
	s_addc_u32 s17, s11, -1
	v_lshlrev_b32_e32 v41, 7, v38
	v_lshlrev_b32_e32 v112, 5, v39
	v_and_b32_e32 v119, 16, v0
	v_and_b32_e32 v120, 8, v0
	v_lshlrev_b32_e32 v0, 6, v37
	v_mov_b32_e32 v123, 0
	s_and_b64 s[10:11], s[16:17], s[10:11]
	v_and_b32_e32 v110, 0xf80, v41
	v_xor_b32_e32 v113, 32, v112
	v_xor_b32_e32 v114, 64, v112
	v_xor_b32_e32 v115, 0x60, v112
	s_sub_i32 s54, s26, 63
	v_lshl_add_u64 v[102:103], v[34:35], 1, s[14:15]
	v_and_b32_e32 v121, 64, v0
	v_bitop3_b32 v122, v0, 64, v0 bitop3:0xc
	s_mov_b32 s14, 0
	v_mov_b32_e32 v124, 0xf149f2ca
	v_mov_b32_e32 v34, 0
	v_mov_b32_e32 v35, v123
	v_mov_b32_e32 v36, v123
	v_mov_b32_e32 v37, v123
	v_mov_b32_e32 v38, v123
	v_mov_b32_e32 v39, v123
	v_mov_b32_e32 v40, v123
	v_mov_b32_e32 v41, v123
	v_mov_b32_e32 v42, v123
	v_mov_b32_e32 v43, v123
	v_mov_b32_e32 v44, v123
	v_mov_b32_e32 v45, v123
	v_mov_b32_e32 v46, v123
	v_mov_b32_e32 v47, v123
	v_mov_b32_e32 v48, v123
	v_mov_b32_e32 v49, v123
	v_mov_b32_e32 v50, 0
	v_mov_b32_e32 v51, v123
	v_mov_b32_e32 v52, v123
	v_mov_b32_e32 v53, v123
	v_mov_b32_e32 v54, v123
	v_mov_b32_e32 v55, v123
	v_mov_b32_e32 v56, v123
	v_mov_b32_e32 v57, v123
	v_mov_b32_e32 v58, v123
	v_mov_b32_e32 v59, v123
	v_mov_b32_e32 v60, v123
	v_mov_b32_e32 v61, v123
	v_mov_b32_e32 v62, v123
	v_mov_b32_e32 v63, v123
	v_mov_b32_e32 v64, v123
	v_mov_b32_e32 v65, v123
	s_mov_b32 s78, 0
	s_mov_b32 s79, 0
	s_mov_b32 s74, 0
	s_mov_b32 s96, 0x42200000
	s_mov_b32 s97, 0x5d800000

.LBB0_1330:
	v_add3_u32 v0, s12, v117, v118
	v_add3_u32 v0, v0, v119, v120
	v_add_u32_e32 v174, v0, v121
	v_add_u32_e32 v175, v0, v122
	ds_read_b64_tr_b16 v[224:225], v174 offset:8192
	ds_read_b64_tr_b16 v[226:227], v174 offset:9216
	ds_read_b64_tr_b16 v[228:229], v175 offset:8192
	ds_read_b64_tr_b16 v[230:231], v175 offset:9216
	ds_read_b64_tr_b16 v[232:233], v174 offset:10240
	ds_read_b64_tr_b16 v[234:235], v174 offset:11264
	ds_read_b64_tr_b16 v[236:237], v175 offset:10240
	ds_read_b64_tr_b16 v[238:239], v175 offset:11264
	s_ff1_i32_b64 s15, s[10:11]
	s_cmp_lg_u64 s[10:11], 0
	s_cselect_b32 s15, s15, -1
	s_cmp_lg_u32 s78, 0
	s_cbranch_scc1 .Lslc_f0
	v_max3_f32 v0, v66, v67, v68
	v_max3_f32 v104, v69, v70, v71
	v_max3_f32 v105, v72, v73, v74
	v_max3_f32 v106, v75, v76, v77
	v_max3_f32 v0, v0, v78, v79
	v_max3_f32 v104, v104, v80, v81
	v_max3_f32 v105, v105, v82, v83
	v_max3_f32 v106, v106, v84, v85
	v_max3_f32 v0, v0, v86, v87
	v_max3_f32 v104, v104, v88, v89
	v_max3_f32 v105, v105, v90, v91
	v_max3_f32 v106, v106, v92, v93
	v_max3_f32 v0, v0, v94, v95
	v_max3_f32 v104, v104, v96, v97
	v_max3_f32 v0, v0, v104, v105
	v_max_f32_e32 v104, v0, v106
	v_mov_b32_e32 v105, v104
	s_nop 1
	v_permlane32_swap_b32 v104, v105
.Lslc_f0:
	s_cmp_lt_i32 s15, 0
	s_cbranch_scc1 .LBB0_1332
	s_cmp_lg_u32 s74, 0
	s_cbranch_scc1 .LBB0_1332
	s_lshl_b32 s16, s15, 6
	s_add_i32 s13, s13, 0xc000
	s_mul_i32 s17, s83, s16
	s_mul_hi_u32 s19, s82, s16
	s_and_b32 s13, s13, 0xc000
	s_add_i32 s17, s19, s17
	s_mul_i32 s16, s82, s16
	s_add_i32 s13, s13, 0
	s_lshl_b64 s[16:17], s[16:17], 1
	v_lshl_add_u64 v[106:107], v[100:101], 0, s[16:17]
	s_add_i32 s13, s92, s13
	s_mov_b32 s19, m0
	s_mov_b32 m0, s13
	s_nop 0
	global_load_lds_dwordx4 v[106:107], off
	s_mov_b32 m0, s19
	v_lshl_add_u64 v[106:107], v[102:103], 0, s[16:17]
	s_addk_i32 s13, 0x2000
	s_mov_b32 s16, m0
	s_mov_b32 m0, s13
	s_nop 0
	global_load_lds_dwordx4 v[106:107], off
	s_mov_b32 m0, s16
.LBB0_1332:
	v_lshrrev_b64 v[106:107], s6, v[98:99]
	v_and_b32_e32 v0, 1, v106
	v_cmp_eq_u64_e64 s[16:17], 0, v[0:1]
	s_cmp_lg_u32 s78, 0
	s_cbranch_scc1 .Lslc_fast
	v_max_f32_e32 v104, v104, v105
	v_cndmask_b32_e64 v105, v104, v182, s[16:17]
	v_sub_f32_e32 v0, v105, v124
	v_cmp_lt_f32_e32 vcc, 0x41000000, v0
	s_cbranch_vccnz .Lslc_rescale

.Lslc_pv:
	s_waitcnt lgkmcnt(12)
	v_mfma_f32_32x32x16_bf16 v[50:65], v[224:227], v[166:169], v[50:65]
	v_mfma_f32_32x32x16_bf16 v[34:49], v[228:231], v[166:169], v[34:49]
	s_waitcnt lgkmcnt(8)
	v_mfma_f32_32x32x16_bf16 v[50:65], v[232:235], v[170:173], v[50:65]
	v_mfma_f32_32x32x16_bf16 v[34:49], v[236:239], v[170:173], v[34:49]
	s_waitcnt lgkmcnt(4)
	v_mfma_f32_32x32x16_bf16 v[50:65], v[240:243], v[248:251], v[50:65]
	v_mfma_f32_32x32x16_bf16 v[34:49], v[244:247], v[248:251], v[34:49]
	s_waitcnt lgkmcnt(0)
	v_mfma_f32_32x32x16_bf16 v[50:65], v[158:161], v[126:129], v[50:65]
	v_mfma_f32_32x32x16_bf16 v[34:49], v[162:165], v[126:129], v[34:49]
	s_cmp_lg_u32 s79, 0
	s_cbranch_scc1 .Lslc_tail
	s_mov_b32 s79, 1
	v_cmp_gt_f32_e64 vcc, |v124|, s96
	s_cbranch_vccnz .Lslc_tail
	s_nop 11
	v_exp_f32_e32 v0, v124
	v_mov_b32_e32 v124, 0
	s_mov_b32 s78, 1
	v_mul_f32_e32 v123, v123, v0
	v_mul_f32_e32 v34, v34, v0
	v_mul_f32_e32 v35, v35, v0
	v_mul_f32_e32 v36, v36, v0
	v_mul_f32_e32 v37, v37, v0
	v_mul_f32_e32 v38, v38, v0
	v_mul_f32_e32 v39, v39, v0
	v_mul_f32_e32 v40, v40, v0
	v_mul_f32_e32 v41, v41, v0
	v_mul_f32_e32 v42, v42, v0
	v_mul_f32_e32 v43, v43, v0
	v_mul_f32_e32 v44, v44, v0
	v_mul_f32_e32 v45, v45, v0
	v_mul_f32_e32 v46, v46, v0
	v_mul_f32_e32 v47, v47, v0
	v_mul_f32_e32 v48, v48, v0
	v_mul_f32_e32 v49, v49, v0
	v_mul_f32_e32 v50, v50, v0
	v_mul_f32_e32 v51, v51, v0
	v_mul_f32_e32 v52, v52, v0
	v_mul_f32_e32 v53, v53, v0
	v_mul_f32_e32 v54, v54, v0
	v_mul_f32_e32 v55, v55, v0
	v_mul_f32_e32 v56, v56, v0
	v_mul_f32_e32 v57, v57, v0
	v_mul_f32_e32 v58, v58, v0
	v_mul_f32_e32 v59, v59, v0
	v_mul_f32_e32 v60, v60, v0
	v_mul_f32_e32 v61, v61, v0
	v_mul_f32_e32 v62, v62, v0
	v_mul_f32_e32 v63, v63, v0
	v_mul_f32_e32 v64, v64, v0
	v_mul_f32_e32 v65, v65, v0
	s_branch .Lslc_tail
.Lslc_fast:
	v_exp_f32_e32 v66, v66
	v_exp_f32_e32 v67, v67
	v_exp_f32_e32 v68, v68
	v_exp_f32_e32 v69, v69
	v_exp_f32_e32 v70, v70
	v_exp_f32_e32 v71, v71
	v_exp_f32_e32 v72, v72
	v_exp_f32_e32 v73, v73
	v_cvt_pk_bf16_f32 v166, v66, v67
	v_cvt_pk_bf16_f32 v167, v68, v69
	v_exp_f32_e32 v74, v74
	v_exp_f32_e32 v75, v75
	v_exp_f32_e32 v76, v76
	v_exp_f32_e32 v77, v77
	v_add_f32_e32 v108, v66, v70
	v_add_f32_e32 v109, v67, v71
	v_add_f32_e32 v178, v68, v72
	v_add_f32_e32 v179, v69, v73
	v_cvt_pk_bf16_f32 v168, v70, v71
	v_cvt_pk_bf16_f32 v169, v72, v73
	ds_read_b64_tr_b16 v[240:241], v174 offset:12288
	ds_read_b64_tr_b16 v[242:243], v174 offset:13312
	ds_read_b64_tr_b16 v[244:245], v175 offset:12288
	ds_read_b64_tr_b16 v[246:247], v175 offset:13312
	v_exp_f32_e32 v78, v78
	v_exp_f32_e32 v79, v79
	v_exp_f32_e32 v80, v80
	v_exp_f32_e32 v81, v81
	v_add_f32_e32 v108, v108, v74
	v_add_f32_e32 v109, v109, v75
	v_add_f32_e32 v178, v178, v76
	v_add_f32_e32 v179, v179, v77
	v_cvt_pk_bf16_f32 v170, v74, v75
	v_cvt_pk_bf16_f32 v171, v76, v77
	v_exp_f32_e32 v82, v82
	v_exp_f32_e32 v83, v83
	v_exp_f32_e32 v84, v84
	v_exp_f32_e32 v85, v85
	v_add_f32_e32 v108, v108, v78
	v_add_f32_e32 v109, v109, v79
	v_add_f32_e32 v178, v178, v80
	v_add_f32_e32 v179, v179, v81
	v_cvt_pk_bf16_f32 v172, v78, v79
	v_cvt_pk_bf16_f32 v173, v80, v81
	ds_read_b64_tr_b16 v[158:159], v174 offset:14336
	ds_read_b64_tr_b16 v[160:161], v174 offset:15360
	ds_read_b64_tr_b16 v[162:163], v175 offset:14336
	ds_read_b64_tr_b16 v[164:165], v175 offset:15360
	v_exp_f32_e32 v86, v86
	v_exp_f32_e32 v87, v87
	v_exp_f32_e32 v88, v88
	v_exp_f32_e32 v89, v89
	v_add_f32_e32 v108, v108, v82
	v_add_f32_e32 v109, v109, v83
	v_add_f32_e32 v178, v178, v84
	v_add_f32_e32 v179, v179, v85
	v_cvt_pk_bf16_f32 v248, v82, v83
	v_cvt_pk_bf16_f32 v249, v84, v85
	v_exp_f32_e32 v90, v90
	v_exp_f32_e32 v91, v91
	v_exp_f32_e32 v92, v92
	v_exp_f32_e32 v93, v93
	v_add_f32_e32 v108, v108, v86
	v_add_f32_e32 v109, v109, v87
	v_add_f32_e32 v178, v178, v88
	v_add_f32_e32 v179, v179, v89
	v_cvt_pk_bf16_f32 v250, v86, v87
	v_cvt_pk_bf16_f32 v251, v88, v89
	v_exp_f32_e32 v94, v94
	v_exp_f32_e32 v95, v95
	v_exp_f32_e32 v96, v96
	v_exp_f32_e32 v97, v97
	v_add_f32_e32 v108, v108, v90
	v_add_f32_e32 v109, v109, v91
	v_add_f32_e32 v178, v178, v92
	v_add_f32_e32 v179, v179, v93
	v_cvt_pk_bf16_f32 v126, v90, v91
	v_cvt_pk_bf16_f32 v127, v92, v93
	v_add_f32_e32 v108, v108, v94
	v_add_f32_e32 v109, v109, v95
	v_add_f32_e32 v178, v178, v96
	v_add_f32_e32 v179, v179, v97
	v_cvt_pk_bf16_f32 v128, v94, v95
	v_cvt_pk_bf16_f32 v129, v96, v97
	v_add_f32_e32 v108, v108, v109
	v_add_f32_e32 v178, v178, v179
	v_add_f32_e32 v108, v108, v178
	v_cndmask_b32_e64 v104, -1, 0, s[16:17]
	v_cndmask_b32_e64 v108, v108, 0, s[16:17]
	v_and_b32_e32 v166, v166, v104
	v_and_b32_e32 v167, v167, v104
	v_and_b32_e32 v168, v168, v104
	v_and_b32_e32 v169, v169, v104
	v_and_b32_e32 v170, v170, v104
	v_and_b32_e32 v171, v171, v104
	v_and_b32_e32 v172, v172, v104
	v_and_b32_e32 v173, v173, v104
	v_and_b32_e32 v248, v248, v104
	v_and_b32_e32 v249, v249, v104
	v_and_b32_e32 v250, v250, v104
	v_and_b32_e32 v251, v251, v104
	v_and_b32_e32 v126, v126, v104
	v_and_b32_e32 v127, v127, v104
	v_and_b32_e32 v128, v128, v104
	v_and_b32_e32 v129, v129, v104
	v_cmp_lt_f32_e32 vcc, s97, v108
	s_cbranch_vccnz .Lslc_fallback
	v_add_f32_e32 v123, v123, v108
	s_branch .Lslc_pv
.Lslc_fallback:
	s_mov_b32 s78, 0
	s_mov_b32 s74, 1
	v_mov_b32_e32 v124, 0
	s_branch .LBB0_1328
.Lslc_tail:
	s_or_b32 s12, s18, s15
	s_cmp_lt_i32 s12, 0
	s_mov_b64 s[12:13], -1
	s_cbranch_scc0 .LBB0_1338
	s_and_b32 s12, s18, s15
	s_cmp_lt_i32 s12, 0
	s_mov_b64 s[12:13], -1
	s_cbranch_scc0 .LBB0_1335
	s_waitcnt vmcnt(0)
	s_mov_b64 s[12:13], 0

.LBB0_1343:
	s_mov_b32 s74, 0
	s_add_u32 s16, s10, -1
	s_addc_u32 s17, s11, -1
	v_mov_b32_e32 v191, v123
	s_andn2_b64 vcc, exec, s[12:13]
	s_and_b64 s[10:11], s[16:17], s[10:11]
	s_cbranch_vccz .LBB0_1345
	s_branch .LBB0_1328
